# stack6 + top-k threshold-search count loops rewritten to 2 VALU per key (both query copies)
# speedup vs baseline: 1.0157x; 1.0053x over previous
.LBB0_2422:
	s_add_i32 s9, s2, s22
	v_mov_b32_e32 v9, 0
	v_mov_b32_e32 v10, 0
	v_cmp_le_u32_e64 s[0:1], s9, v2
	v_cmp_le_u32_e64 s[2:3], s9, v3
	v_cmp_le_u32_e64 s[98:99], s9, v1
	v_addc_co_u32_e64 v9, s[100:101], 0, v9, s[0:1]
	v_cmp_le_u32_e64 s[0:1], s9, v8
	v_addc_co_u32_e64 v10, s[100:101], 0, v10, s[2:3]
	v_cmp_le_u32_e64 s[2:3], s9, v6
	v_addc_co_u32_e64 v9, s[100:101], 0, v9, s[98:99]
	v_cmp_le_u32_e64 s[98:99], s9, v7
	v_addc_co_u32_e64 v10, s[100:101], 0, v10, s[0:1]
	v_cmp_le_u32_e64 s[0:1], s9, v5
	v_addc_co_u32_e64 v9, s[100:101], 0, v9, s[2:3]
	v_cmp_le_u32_e64 s[2:3], s9, v4
	v_addc_co_u32_e64 v10, s[100:101], 0, v10, s[98:99]
	v_addc_co_u32_e64 v9, s[100:101], 0, v9, s[0:1]
	v_addc_co_u32_e64 v10, s[100:101], 0, v10, s[2:3]
	v_add_u32_e32 v9, v10, v9
	s_and_b64 vcc, exec, s[14:15]
	s_nop 0
	s_cbranch_vccz .LBB0_2428
	s_and_b64 vcc, exec, s[12:13]
	s_cbranch_vccz .LBB0_2429

.LBB0_2425:
	v_cmp_le_u32_e64 s[0:1], s9, v34
	v_cmp_le_u32_e64 s[2:3], s9, v36
	v_cmp_le_u32_e64 s[98:99], s9, v38
	v_addc_co_u32_e64 v9, s[100:101], 0, v9, s[0:1]
	v_cmp_le_u32_e64 s[0:1], s9, v39
	v_addc_co_u32_e64 v9, s[100:101], 0, v9, s[2:3]
	v_cmp_le_u32_e64 s[2:3], s9, v32
	v_addc_co_u32_e64 v9, s[100:101], 0, v9, s[98:99]
	v_cmp_le_u32_e64 s[98:99], s9, v33
	v_addc_co_u32_e64 v9, s[100:101], 0, v9, s[0:1]
	v_cmp_le_u32_e64 s[0:1], s9, v35
	v_addc_co_u32_e64 v9, s[100:101], 0, v9, s[2:3]
	v_cmp_le_u32_e64 s[2:3], s9, v37
	v_addc_co_u32_e64 v9, s[100:101], 0, v9, s[98:99]
	v_addc_co_u32_e64 v9, s[100:101], 0, v9, s[0:1]
	v_addc_co_u32_e64 v9, s[100:101], 0, v9, s[2:3]

.LBB0_2428:
	v_cmp_le_u32_e64 s[0:1], s9, v18
	v_cmp_le_u32_e64 s[2:3], s9, v21
	v_cmp_le_u32_e64 s[98:99], s9, v22
	v_addc_co_u32_e64 v9, s[100:101], 0, v9, s[0:1]
	v_cmp_le_u32_e64 s[0:1], s9, v23
	v_addc_co_u32_e64 v9, s[100:101], 0, v9, s[2:3]
	v_cmp_le_u32_e64 s[2:3], s9, v16
	v_addc_co_u32_e64 v9, s[100:101], 0, v9, s[98:99]
	v_cmp_le_u32_e64 s[98:99], s9, v17
	v_addc_co_u32_e64 v9, s[100:101], 0, v9, s[0:1]
	v_cmp_le_u32_e64 s[0:1], s9, v19
	v_addc_co_u32_e64 v9, s[100:101], 0, v9, s[2:3]
	v_cmp_le_u32_e64 s[2:3], s9, v20
	v_addc_co_u32_e64 v9, s[100:101], 0, v9, s[98:99]
	v_addc_co_u32_e64 v9, s[100:101], 0, v9, s[0:1]
	v_addc_co_u32_e64 v9, s[100:101], 0, v9, s[2:3]
	s_and_b64 vcc, exec, s[12:13]
	s_cbranch_vccnz .LBB0_2424
.LBB0_2429:
	v_cmp_le_u32_e64 s[0:1], s9, v26
	v_cmp_le_u32_e64 s[2:3], s9, v28
	v_cmp_le_u32_e64 s[98:99], s9, v30
	v_addc_co_u32_e64 v9, s[100:101], 0, v9, s[0:1]
	v_cmp_le_u32_e64 s[0:1], s9, v31
	v_addc_co_u32_e64 v9, s[100:101], 0, v9, s[2:3]
	v_cmp_le_u32_e64 s[2:3], s9, v24
	v_addc_co_u32_e64 v9, s[100:101], 0, v9, s[98:99]
	v_cmp_le_u32_e64 s[98:99], s9, v25
	v_addc_co_u32_e64 v9, s[100:101], 0, v9, s[0:1]
	v_cmp_le_u32_e64 s[0:1], s9, v27
	v_addc_co_u32_e64 v9, s[100:101], 0, v9, s[2:3]
	v_cmp_le_u32_e64 s[2:3], s9, v29
	v_addc_co_u32_e64 v9, s[100:101], 0, v9, s[98:99]
	v_addc_co_u32_e64 v9, s[100:101], 0, v9, s[0:1]
	v_addc_co_u32_e64 v9, s[100:101], 0, v9, s[2:3]
	s_and_b64 vcc, exec, s[10:11]
	s_cbranch_vccz .LBB0_2425
	s_branch .LBB0_2426

.LBB0_2734:
	s_add_i32 s8, s2, s18
	v_mov_b32_e32 v37, 0
	v_mov_b32_e32 v38, 0
	v_cmp_le_u32_e64 s[0:1], s8, v2
	v_cmp_le_u32_e64 s[2:3], s8, v3
	v_cmp_le_u32_e64 s[98:99], s8, v1
	v_addc_co_u32_e64 v37, s[100:101], 0, v37, s[0:1]
	v_cmp_le_u32_e64 s[0:1], s8, v18
	v_addc_co_u32_e64 v38, s[100:101], 0, v38, s[2:3]
	v_cmp_le_u32_e64 s[2:3], s8, v6
	v_addc_co_u32_e64 v37, s[100:101], 0, v37, s[98:99]
	v_cmp_le_u32_e64 s[98:99], s8, v7
	v_addc_co_u32_e64 v38, s[100:101], 0, v38, s[0:1]
	v_cmp_le_u32_e64 s[0:1], s8, v5
	v_addc_co_u32_e64 v37, s[100:101], 0, v37, s[2:3]
	v_cmp_le_u32_e64 s[2:3], s8, v4
	v_addc_co_u32_e64 v38, s[100:101], 0, v38, s[98:99]
	v_cmp_le_u32_e64 s[98:99], s8, v9
	v_addc_co_u32_e64 v37, s[100:101], 0, v37, s[0:1]
	v_cmp_le_u32_e64 s[0:1], s8, v8
	v_addc_co_u32_e64 v38, s[100:101], 0, v38, s[2:3]
	v_cmp_le_u32_e64 s[2:3], s8, v10
	v_addc_co_u32_e64 v37, s[100:101], 0, v37, s[98:99]
	v_cmp_le_u32_e64 s[98:99], s8, v11
	v_addc_co_u32_e64 v38, s[100:101], 0, v38, s[0:1]
	v_cmp_le_u32_e64 s[0:1], s8, v14
	v_addc_co_u32_e64 v37, s[100:101], 0, v37, s[2:3]
	v_cmp_le_u32_e64 s[2:3], s8, v15
	v_addc_co_u32_e64 v38, s[100:101], 0, v38, s[98:99]
	v_cmp_le_u32_e64 s[98:99], s8, v13
	v_addc_co_u32_e64 v37, s[100:101], 0, v37, s[0:1]
	v_cmp_le_u32_e64 s[0:1], s8, v12
	v_addc_co_u32_e64 v38, s[100:101], 0, v38, s[2:3]
	v_cmp_le_u32_e64 s[2:3], s8, v33
	v_addc_co_u32_e64 v37, s[100:101], 0, v37, s[98:99]
	v_cmp_le_u32_e64 s[98:99], s8, v34
	v_addc_co_u32_e64 v38, s[100:101], 0, v38, s[0:1]
	v_cmp_le_u32_e64 s[0:1], s8, v36
	v_addc_co_u32_e64 v37, s[100:101], 0, v37, s[2:3]
	v_cmp_le_u32_e64 s[2:3], s8, v35
	v_addc_co_u32_e64 v38, s[100:101], 0, v38, s[98:99]
	v_cmp_le_u32_e64 s[98:99], s8, v30
	v_addc_co_u32_e64 v37, s[100:101], 0, v37, s[0:1]
	v_cmp_le_u32_e64 s[0:1], s8, v29
	v_addc_co_u32_e64 v38, s[100:101], 0, v38, s[2:3]
	v_cmp_le_u32_e64 s[2:3], s8, v31
	v_addc_co_u32_e64 v37, s[100:101], 0, v37, s[98:99]
	v_cmp_le_u32_e64 s[98:99], s8, v32
	v_addc_co_u32_e64 v38, s[100:101], 0, v38, s[0:1]
	v_cmp_le_u32_e64 s[0:1], s8, v24
	v_addc_co_u32_e64 v37, s[100:101], 0, v37, s[2:3]
	v_cmp_le_u32_e64 s[2:3], s8, v23
	v_addc_co_u32_e64 v38, s[100:101], 0, v38, s[98:99]
	v_cmp_le_u32_e64 s[98:99], s8, v27
	v_addc_co_u32_e64 v37, s[100:101], 0, v37, s[0:1]
	v_cmp_le_u32_e64 s[0:1], s8, v28
	v_addc_co_u32_e64 v38, s[100:101], 0, v38, s[2:3]
	v_cmp_le_u32_e64 s[2:3], s8, v25
	v_addc_co_u32_e64 v37, s[100:101], 0, v37, s[98:99]
	v_cmp_le_u32_e64 s[98:99], s8, v26
	v_addc_co_u32_e64 v38, s[100:101], 0, v38, s[0:1]
	v_cmp_le_u32_e64 s[0:1], s8, v22
	v_addc_co_u32_e64 v37, s[100:101], 0, v37, s[2:3]
	v_cmp_le_u32_e64 s[2:3], s8, v21
	v_addc_co_u32_e64 v38, s[100:101], 0, v38, s[98:99]
	v_cmp_le_u32_e64 s[98:99], s8, v16
	v_addc_co_u32_e64 v37, s[100:101], 0, v37, s[0:1]
	v_cmp_le_u32_e64 s[0:1], s8, v17
	v_addc_co_u32_e64 v38, s[100:101], 0, v38, s[2:3]
	v_cmp_le_u32_e64 s[2:3], s8, v19
	v_addc_co_u32_e64 v37, s[100:101], 0, v37, s[98:99]
	v_cmp_le_u32_e64 s[98:99], s8, v20
	v_addc_co_u32_e64 v38, s[100:101], 0, v38, s[0:1]
	v_cmp_le_u32_e64 s[0:1], s8, v50
	v_addc_co_u32_e64 v37, s[100:101], 0, v37, s[2:3]
	v_cmp_le_u32_e64 s[2:3], s8, v74
	v_addc_co_u32_e64 v38, s[100:101], 0, v38, s[98:99]
	v_cmp_le_u32_e64 s[98:99], s8, v75
	v_addc_co_u32_e64 v37, s[100:101], 0, v37, s[0:1]
	v_cmp_le_u32_e64 s[0:1], s8, v47
	v_addc_co_u32_e64 v38, s[100:101], 0, v38, s[2:3]
	v_addc_co_u32_e64 v37, s[100:101], 0, v37, s[98:99]
	v_addc_co_u32_e64 v38, s[100:101], 0, v38, s[0:1]
	v_add_u32_e32 v37, v38, v37
	s_and_b64 vcc, exec, s[14:15]
	s_cbranch_vccz .LBB0_2740
	s_and_b64 vcc, exec, s[12:13]
	s_cbranch_vccz .LBB0_2741

.LBB0_2737:
	v_cmp_le_u32_e64 s[0:1], s8, v68
	v_cmp_le_u32_e64 s[2:3], s8, v70
	v_cmp_le_u32_e64 s[98:99], s8, v72
	v_addc_co_u32_e64 v37, s[100:101], 0, v37, s[0:1]
	v_cmp_le_u32_e64 s[0:1], s8, v73
	v_addc_co_u32_e64 v37, s[100:101], 0, v37, s[2:3]
	v_cmp_le_u32_e64 s[2:3], s8, v66
	v_addc_co_u32_e64 v37, s[100:101], 0, v37, s[98:99]
	v_cmp_le_u32_e64 s[98:99], s8, v67
	v_addc_co_u32_e64 v37, s[100:101], 0, v37, s[0:1]
	v_cmp_le_u32_e64 s[0:1], s8, v69
	v_addc_co_u32_e64 v37, s[100:101], 0, v37, s[2:3]
	v_cmp_le_u32_e64 s[2:3], s8, v71
	v_addc_co_u32_e64 v37, s[100:101], 0, v37, s[98:99]
	v_addc_co_u32_e64 v37, s[100:101], 0, v37, s[0:1]
	v_addc_co_u32_e64 v37, s[100:101], 0, v37, s[2:3]

.LBB0_2740:
	v_cmp_le_u32_e64 s[0:1], s8, v52
	v_cmp_le_u32_e64 s[2:3], s8, v54
	v_cmp_le_u32_e64 s[98:99], s8, v56
	v_addc_co_u32_e64 v37, s[100:101], 0, v37, s[0:1]
	v_cmp_le_u32_e64 s[0:1], s8, v57
	v_addc_co_u32_e64 v37, s[100:101], 0, v37, s[2:3]
	v_cmp_le_u32_e64 s[2:3], s8, v49
	v_addc_co_u32_e64 v37, s[100:101], 0, v37, s[98:99]
	v_cmp_le_u32_e64 s[98:99], s8, v51
	v_addc_co_u32_e64 v37, s[100:101], 0, v37, s[0:1]
	v_cmp_le_u32_e64 s[0:1], s8, v53
	v_addc_co_u32_e64 v37, s[100:101], 0, v37, s[2:3]
	v_cmp_le_u32_e64 s[2:3], s8, v55
	v_addc_co_u32_e64 v37, s[100:101], 0, v37, s[98:99]
	v_addc_co_u32_e64 v37, s[100:101], 0, v37, s[0:1]
	v_addc_co_u32_e64 v37, s[100:101], 0, v37, s[2:3]
	s_and_b64 vcc, exec, s[12:13]
	s_cbranch_vccnz .LBB0_2736
.LBB0_2741:
	v_cmp_le_u32_e64 s[0:1], s8, v60
	v_cmp_le_u32_e64 s[2:3], s8, v62
	v_cmp_le_u32_e64 s[98:99], s8, v64
	v_addc_co_u32_e64 v37, s[100:101], 0, v37, s[0:1]
	v_cmp_le_u32_e64 s[0:1], s8, v65
	v_addc_co_u32_e64 v37, s[100:101], 0, v37, s[2:3]
	v_cmp_le_u32_e64 s[2:3], s8, v58
	v_addc_co_u32_e64 v37, s[100:101], 0, v37, s[98:99]
	v_cmp_le_u32_e64 s[98:99], s8, v59
	v_addc_co_u32_e64 v37, s[100:101], 0, v37, s[0:1]
	v_cmp_le_u32_e64 s[0:1], s8, v61
	v_addc_co_u32_e64 v37, s[100:101], 0, v37, s[2:3]
	v_cmp_le_u32_e64 s[2:3], s8, v63
	v_addc_co_u32_e64 v37, s[100:101], 0, v37, s[98:99]
	v_addc_co_u32_e64 v37, s[100:101], 0, v37, s[0:1]
	v_addc_co_u32_e64 v37, s[100:101], 0, v37, s[2:3]
	s_and_b64 vcc, exec, s[10:11]
	s_cbranch_vccz .LBB0_2737
	s_branch .LBB0_2738

	.amdhsa_kernel _ZN2mk4megaENS_6ParamsE
		.amdhsa_group_segment_fixed_size 0
		.amdhsa_private_segment_fixed_size 0
		.amdhsa_kernarg_size 920
		.amdhsa_user_sgpr_count 2
		.amdhsa_user_sgpr_dispatch_ptr 0
		.amdhsa_user_sgpr_queue_ptr 0
		.amdhsa_user_sgpr_kernarg_segment_ptr 1
		.amdhsa_user_sgpr_dispatch_id 0
		.amdhsa_user_sgpr_kernarg_preload_length 0
		.amdhsa_user_sgpr_kernarg_preload_offset 0
		.amdhsa_user_sgpr_private_segment_size 0
		.amdhsa_uses_dynamic_stack 0
		.amdhsa_enable_private_segment 0
		.amdhsa_system_sgpr_workgroup_id_x 1
		.amdhsa_system_sgpr_workgroup_id_y 0
		.amdhsa_system_sgpr_workgroup_id_z 0
		.amdhsa_system_sgpr_workgroup_info 0
		.amdhsa_system_vgpr_workitem_id 0
		.amdhsa_next_free_vgpr 256
		.amdhsa_next_free_sgpr 102
		.amdhsa_accum_offset 256
		.amdhsa_reserve_vcc 1
		.amdhsa_float_round_mode_32 0
		.amdhsa_float_round_mode_16_64 0
		.amdhsa_float_denorm_mode_32 3
		.amdhsa_float_denorm_mode_16_64 3
		.amdhsa_dx10_clamp 1
		.amdhsa_ieee_mode 1
		.amdhsa_fp16_overflow 0
		.amdhsa_tg_split 0
		.amdhsa_exception_fp_ieee_invalid_op 0
		.amdhsa_exception_fp_denorm_src 0
		.amdhsa_exception_fp_ieee_div_zero 0
		.amdhsa_exception_fp_ieee_overflow 0
		.amdhsa_exception_fp_ieee_underflow 0
		.amdhsa_exception_fp_ieee_inexact 0
		.amdhsa_exception_int_div_zero 0
	.end_amdhsa_kernel

amdhsa.kernels:
  - .agpr_count:     0
    .args:
      - .offset:         0
        .size:           664
        .value_kind:     by_value
      - .offset:         664
        .size:           4
        .value_kind:     hidden_block_count_x
      - .offset:         668
        .size:           4
        .value_kind:     hidden_block_count_y
      - .offset:         672
        .size:           4
        .value_kind:     hidden_block_count_z
      - .offset:         676
        .size:           2
        .value_kind:     hidden_group_size_x
      - .offset:         678
        .size:           2
        .value_kind:     hidden_group_size_y
      - .offset:         680
        .size:           2
        .value_kind:     hidden_group_size_z
      - .offset:         682
        .size:           2
        .value_kind:     hidden_remainder_x
      - .offset:         684
        .size:           2
        .value_kind:     hidden_remainder_y
      - .offset:         686
        .size:           2
        .value_kind:     hidden_remainder_z
      - .offset:         704
        .size:           8
        .value_kind:     hidden_global_offset_x
      - .offset:         712
        .size:           8
        .value_kind:     hidden_global_offset_y
      - .offset:         720
        .size:           8
        .value_kind:     hidden_global_offset_z
      - .offset:         728
        .size:           2
        .value_kind:     hidden_grid_dims
      - .offset:         784
        .size:           4
        .value_kind:     hidden_dynamic_lds_size
    .group_segment_fixed_size: 0
    .kernarg_segment_align: 8
    .kernarg_segment_size: 920
    .language:       OpenCL C
    .language_version:
      - 2
      - 0
    .max_flat_workgroup_size: 512
    .name:           _ZN2mk4megaENS_6ParamsE
    .private_segment_fixed_size: 0
    .sgpr_count:     108
    .sgpr_spill_count: 277
    .symbol:         _ZN2mk4megaENS_6ParamsE.kd
    .uniform_work_group_size: 1
    .uses_dynamic_stack: false
    .vgpr_count:     256
    .vgpr_spill_count: 0
    .wavefront_size: 64
